# adaLN k-loop rewritten by hand: f32 v_fmac with DPP quad_perm broadcast of silu(c), b128 LDS reads, W rows double-buffered across iterations (same f32 math, sequential fma order)
# baseline (speedup 1.0000x reference)
; #define LAS __attribute__((address_space(3)))
; __device__ __forceinline__ void adaln_unit(const Args& a, LAS unsigned char* lds, int unit, int tid, int wave, int lane) {
;     ...
;     for (int kh = 0; kh < 2; ++kh) {
;         __syncthreads();
;         for (int i = tid; i < 18 * 1024; i += NTHR) { const int r = i >> 10, k = (i & 1023) + kh * 1024; const float c = r < 2 ? a.in[I_CP][r * 2048 + k] : a.in[I_CS][(r - 2) * 2048 + k];
;             sc[i] = c / (1.0f + __expf(-c)); }
;         __syncthreads();
;         const int kb = wave * 128;
;         for (int k = 0; k < 128; k += 16) {
;             float w[16];
; #pragma unroll
;             for (int e = 0; e < 16; ++e) w[e] = W[(size_t)(kh * 1024 + kb + k + e) * N + jc];
; #pragma unroll
;             for (int q = 0; q < 4; ++q)
; #pragma unroll
;                 for (int r = 0; r < 18; ++r) { const f32x4 s = *(const LAS f32x4*)(sc + r * 1024 + kb + k + 4 * q); acc[r] += s[0] * w[4 * q] + s[1] * w[4 * q + 1] + s[2] * w[4 * q + 2] + s[3] * w[4 * q + 3]; }
.LBB0_19:
	s_or_b64 exec, exec, s[80:81]
	s_add_i32 s34, s58, s24
	v_mov_b32_e32 v2, s34
	s_xor_b64 s[80:81], s[82:83], -1
	v_mad_u64_u32 v[44:45], s[82:83], s74, v2, v[42:43]
	s_mov_b32 s82, -16
	s_mov_b32 s83, s30
	s_waitcnt lgkmcnt(0)
	s_barrier
	s_nop 0
	v_readfirstlane_b32 s84, v44
	v_readfirstlane_b32 s85, v45
	v_mbcnt_lo_u32_b32 v135, -1, 0
	v_mbcnt_hi_u32_b32 v135, -1, v135
	v_subrev_u32_e32 v132, s84, v44
	v_and_b32_e32 v135, 3, v135
	v_lshlrev_b32_e32 v135, 4, v135
	v_add_u32_e32 v134, s83, v135
	v_add_u32_e32 v133, 0xffff0000, v134
	s_mov_b32 s82, 0
	global_load_dword v64, v132, s[84:85]
	s_add_u32 s84, s84, s74
	s_addc_u32 s85, s85, s75
	global_load_dword v65, v132, s[84:85]
	s_add_u32 s84, s84, s74
	s_addc_u32 s85, s85, s75
	global_load_dword v66, v132, s[84:85]
	s_add_u32 s84, s84, s74
	s_addc_u32 s85, s85, s75
	global_load_dword v67, v132, s[84:85]
	s_add_u32 s84, s84, s74
	s_addc_u32 s85, s85, s75
	global_load_dword v68, v132, s[84:85]
	s_add_u32 s84, s84, s74
	s_addc_u32 s85, s85, s75
	global_load_dword v69, v132, s[84:85]
	s_add_u32 s84, s84, s74
	s_addc_u32 s85, s85, s75
	global_load_dword v70, v132, s[84:85]
	s_add_u32 s84, s84, s74
	s_addc_u32 s85, s85, s75
	global_load_dword v71, v132, s[84:85]
	s_add_u32 s84, s84, s74
	s_addc_u32 s85, s85, s75
	global_load_dword v72, v132, s[84:85]
	s_add_u32 s84, s84, s74
	s_addc_u32 s85, s85, s75
	global_load_dword v73, v132, s[84:85]
	s_add_u32 s84, s84, s74
	s_addc_u32 s85, s85, s75
	global_load_dword v74, v132, s[84:85]
	s_add_u32 s84, s84, s74
	s_addc_u32 s85, s85, s75
	global_load_dword v75, v132, s[84:85]
	s_add_u32 s84, s84, s74
	s_addc_u32 s85, s85, s75
	global_load_dword v76, v132, s[84:85]
	s_add_u32 s84, s84, s74
	s_addc_u32 s85, s85, s75
	global_load_dword v77, v132, s[84:85]
	s_add_u32 s84, s84, s74
	s_addc_u32 s85, s85, s75
	global_load_dword v78, v132, s[84:85]
	s_add_u32 s84, s84, s74
	s_addc_u32 s85, s85, s75
	global_load_dword v79, v132, s[84:85]
	s_add_u32 s84, s84, s74
	s_addc_u32 s85, s85, s75
	ds_read_b128 v[96:99], v133 offset:0
	ds_read_b128 v[100:103], v133 offset:4096
	ds_read_b128 v[104:107], v133 offset:8192
	ds_read_b128 v[108:111], v133 offset:12288
	ds_read_b128 v[112:115], v133 offset:16384
	ds_read_b128 v[116:119], v133 offset:20480
	ds_read_b128 v[120:123], v133 offset:24576
	ds_read_b128 v[124:127], v133 offset:28672
	ds_read_b128 v[128:131], v133 offset:32768
	ds_read_b128 v[2:5], v133 offset:36864
	ds_read_b128 v[6:9], v133 offset:40960
	ds_read_b128 v[10:13], v133 offset:45056
	ds_read_b128 v[14:17], v133 offset:49152
	ds_read_b128 v[18:21], v133 offset:53248
	ds_read_b128 v[22:25], v133 offset:57344
	ds_read_b128 v[26:29], v133 offset:61440
	ds_read_b128 v[30:33], v134 offset:0
	ds_read_b128 v[34:37], v134 offset:4096
.Lada_loop:
	global_load_dword v80, v132, s[84:85]
	s_add_u32 s84, s84, s74
	s_addc_u32 s85, s85, s75
	global_load_dword v81, v132, s[84:85]
	s_add_u32 s84, s84, s74
	s_addc_u32 s85, s85, s75
	global_load_dword v82, v132, s[84:85]
	s_add_u32 s84, s84, s74
	s_addc_u32 s85, s85, s75
	global_load_dword v83, v132, s[84:85]
	s_add_u32 s84, s84, s74
	s_addc_u32 s85, s85, s75
	global_load_dword v84, v132, s[84:85]
	s_add_u32 s84, s84, s74
	s_addc_u32 s85, s85, s75
	global_load_dword v85, v132, s[84:85]
	s_add_u32 s84, s84, s74
	s_addc_u32 s85, s85, s75
	global_load_dword v86, v132, s[84:85]
	s_add_u32 s84, s84, s74
	s_addc_u32 s85, s85, s75
	global_load_dword v87, v132, s[84:85]
	s_add_u32 s84, s84, s74
	s_addc_u32 s85, s85, s75
	global_load_dword v88, v132, s[84:85]
	s_add_u32 s84, s84, s74
	s_addc_u32 s85, s85, s75
	global_load_dword v89, v132, s[84:85]
	s_add_u32 s84, s84, s74
	s_addc_u32 s85, s85, s75
	global_load_dword v90, v132, s[84:85]
	s_add_u32 s84, s84, s74
	s_addc_u32 s85, s85, s75
	global_load_dword v91, v132, s[84:85]
	s_add_u32 s84, s84, s74
	s_addc_u32 s85, s85, s75
	global_load_dword v92, v132, s[84:85]
	s_add_u32 s84, s84, s74
	s_addc_u32 s85, s85, s75
	global_load_dword v93, v132, s[84:85]
	s_add_u32 s84, s84, s74
	s_addc_u32 s85, s85, s75
	global_load_dword v94, v132, s[84:85]
	s_add_u32 s84, s84, s74
	s_addc_u32 s85, s85, s75
	global_load_dword v95, v132, s[84:85]
	s_add_u32 s84, s84, s74
	s_addc_u32 s85, s85, s75
	s_waitcnt vmcnt(16) lgkmcnt(9)
; #define LAS __attribute__((address_space(3)))
; __device__ __forceinline__ void adaln_unit(const Args& a, LAS unsigned char* lds, int unit, int tid, int wave, int lane) {
;     ...
;         for (int k = 0; k < 128; k += 16) {
;             float w[16];
; #pragma unroll
;             for (int e = 0; e < 16; ++e) w[e] = W[(size_t)(kh * 1024 + kb + k + e) * N + jc];
; #pragma unroll
;             for (int q = 0; q < 4; ++q)
; #pragma unroll
;                 for (int r = 0; r < 18; ++r) { const f32x4 s = *(const LAS f32x4*)(sc + r * 1024 + kb + k + 4 * q); acc[r] += s[0] * w[4 * q] + s[1] * w[4 * q + 1] + s[2] * w[4 * q + 2] + s[3] * w[4 * q + 3]; }
	v_fmac_f32_dpp v63, v96, v64 quad_perm:[0,0,0,0] row_mask:0xf bank_mask:0xf
	v_fmac_f32_dpp v62, v100, v64 quad_perm:[0,0,0,0] row_mask:0xf bank_mask:0xf
	v_fmac_f32_dpp v61, v104, v64 quad_perm:[0,0,0,0] row_mask:0xf bank_mask:0xf
	v_fmac_f32_dpp v60, v108, v64 quad_perm:[0,0,0,0] row_mask:0xf bank_mask:0xf
	v_fmac_f32_dpp v59, v112, v64 quad_perm:[0,0,0,0] row_mask:0xf bank_mask:0xf
	v_fmac_f32_dpp v58, v116, v64 quad_perm:[0,0,0,0] row_mask:0xf bank_mask:0xf
	v_fmac_f32_dpp v57, v120, v64 quad_perm:[0,0,0,0] row_mask:0xf bank_mask:0xf
	v_fmac_f32_dpp v56, v124, v64 quad_perm:[0,0,0,0] row_mask:0xf bank_mask:0xf
	v_fmac_f32_dpp v55, v128, v64 quad_perm:[0,0,0,0] row_mask:0xf bank_mask:0xf
	v_fmac_f32_dpp v63, v97, v65 quad_perm:[0,0,0,0] row_mask:0xf bank_mask:0xf
	v_fmac_f32_dpp v62, v101, v65 quad_perm:[0,0,0,0] row_mask:0xf bank_mask:0xf
	v_fmac_f32_dpp v61, v105, v65 quad_perm:[0,0,0,0] row_mask:0xf bank_mask:0xf
	v_fmac_f32_dpp v60, v109, v65 quad_perm:[0,0,0,0] row_mask:0xf bank_mask:0xf
	v_fmac_f32_dpp v59, v113, v65 quad_perm:[0,0,0,0] row_mask:0xf bank_mask:0xf
	v_fmac_f32_dpp v58, v117, v65 quad_perm:[0,0,0,0] row_mask:0xf bank_mask:0xf
	v_fmac_f32_dpp v57, v121, v65 quad_perm:[0,0,0,0] row_mask:0xf bank_mask:0xf
	v_fmac_f32_dpp v56, v125, v65 quad_perm:[0,0,0,0] row_mask:0xf bank_mask:0xf
	v_fmac_f32_dpp v55, v129, v65 quad_perm:[0,0,0,0] row_mask:0xf bank_mask:0xf
	v_fmac_f32_dpp v63, v98, v66 quad_perm:[0,0,0,0] row_mask:0xf bank_mask:0xf
	v_fmac_f32_dpp v62, v102, v66 quad_perm:[0,0,0,0] row_mask:0xf bank_mask:0xf
	v_fmac_f32_dpp v61, v106, v66 quad_perm:[0,0,0,0] row_mask:0xf bank_mask:0xf
	v_fmac_f32_dpp v60, v110, v66 quad_perm:[0,0,0,0] row_mask:0xf bank_mask:0xf
	v_fmac_f32_dpp v59, v114, v66 quad_perm:[0,0,0,0] row_mask:0xf bank_mask:0xf
	v_fmac_f32_dpp v58, v118, v66 quad_perm:[0,0,0,0] row_mask:0xf bank_mask:0xf
	v_fmac_f32_dpp v57, v122, v66 quad_perm:[0,0,0,0] row_mask:0xf bank_mask:0xf
	v_fmac_f32_dpp v56, v126, v66 quad_perm:[0,0,0,0] row_mask:0xf bank_mask:0xf
	v_fmac_f32_dpp v55, v130, v66 quad_perm:[0,0,0,0] row_mask:0xf bank_mask:0xf
	v_fmac_f32_dpp v63, v99, v67 quad_perm:[0,0,0,0] row_mask:0xf bank_mask:0xf
	v_fmac_f32_dpp v62, v103, v67 quad_perm:[0,0,0,0] row_mask:0xf bank_mask:0xf
	v_fmac_f32_dpp v61, v107, v67 quad_perm:[0,0,0,0] row_mask:0xf bank_mask:0xf
	v_fmac_f32_dpp v60, v111, v67 quad_perm:[0,0,0,0] row_mask:0xf bank_mask:0xf
	v_fmac_f32_dpp v59, v115, v67 quad_perm:[0,0,0,0] row_mask:0xf bank_mask:0xf
	v_fmac_f32_dpp v58, v119, v67 quad_perm:[0,0,0,0] row_mask:0xf bank_mask:0xf
	v_fmac_f32_dpp v57, v123, v67 quad_perm:[0,0,0,0] row_mask:0xf bank_mask:0xf
	v_fmac_f32_dpp v56, v127, v67 quad_perm:[0,0,0,0] row_mask:0xf bank_mask:0xf
	v_fmac_f32_dpp v55, v131, v67 quad_perm:[0,0,0,0] row_mask:0xf bank_mask:0xf
	v_fmac_f32_dpp v63, v96, v68 quad_perm:[1,1,1,1] row_mask:0xf bank_mask:0xf
	v_fmac_f32_dpp v62, v100, v68 quad_perm:[1,1,1,1] row_mask:0xf bank_mask:0xf
	v_fmac_f32_dpp v61, v104, v68 quad_perm:[1,1,1,1] row_mask:0xf bank_mask:0xf
	v_fmac_f32_dpp v60, v108, v68 quad_perm:[1,1,1,1] row_mask:0xf bank_mask:0xf
	v_fmac_f32_dpp v59, v112, v68 quad_perm:[1,1,1,1] row_mask:0xf bank_mask:0xf
	v_fmac_f32_dpp v58, v116, v68 quad_perm:[1,1,1,1] row_mask:0xf bank_mask:0xf
	v_fmac_f32_dpp v57, v120, v68 quad_perm:[1,1,1,1] row_mask:0xf bank_mask:0xf
	v_fmac_f32_dpp v56, v124, v68 quad_perm:[1,1,1,1] row_mask:0xf bank_mask:0xf
	v_fmac_f32_dpp v55, v128, v68 quad_perm:[1,1,1,1] row_mask:0xf bank_mask:0xf
	v_fmac_f32_dpp v63, v97, v69 quad_perm:[1,1,1,1] row_mask:0xf bank_mask:0xf
	v_fmac_f32_dpp v62, v101, v69 quad_perm:[1,1,1,1] row_mask:0xf bank_mask:0xf
	v_fmac_f32_dpp v61, v105, v69 quad_perm:[1,1,1,1] row_mask:0xf bank_mask:0xf
	v_fmac_f32_dpp v60, v109, v69 quad_perm:[1,1,1,1] row_mask:0xf bank_mask:0xf
	v_fmac_f32_dpp v59, v113, v69 quad_perm:[1,1,1,1] row_mask:0xf bank_mask:0xf
	v_fmac_f32_dpp v58, v117, v69 quad_perm:[1,1,1,1] row_mask:0xf bank_mask:0xf
	v_fmac_f32_dpp v57, v121, v69 quad_perm:[1,1,1,1] row_mask:0xf bank_mask:0xf
	v_fmac_f32_dpp v56, v125, v69 quad_perm:[1,1,1,1] row_mask:0xf bank_mask:0xf
	v_fmac_f32_dpp v55, v129, v69 quad_perm:[1,1,1,1] row_mask:0xf bank_mask:0xf
	v_fmac_f32_dpp v63, v98, v70 quad_perm:[1,1,1,1] row_mask:0xf bank_mask:0xf
	v_fmac_f32_dpp v62, v102, v70 quad_perm:[1,1,1,1] row_mask:0xf bank_mask:0xf
	v_fmac_f32_dpp v61, v106, v70 quad_perm:[1,1,1,1] row_mask:0xf bank_mask:0xf
	v_fmac_f32_dpp v60, v110, v70 quad_perm:[1,1,1,1] row_mask:0xf bank_mask:0xf
	v_fmac_f32_dpp v59, v114, v70 quad_perm:[1,1,1,1] row_mask:0xf bank_mask:0xf
	v_fmac_f32_dpp v58, v118, v70 quad_perm:[1,1,1,1] row_mask:0xf bank_mask:0xf
	v_fmac_f32_dpp v57, v122, v70 quad_perm:[1,1,1,1] row_mask:0xf bank_mask:0xf
	v_fmac_f32_dpp v56, v126, v70 quad_perm:[1,1,1,1] row_mask:0xf bank_mask:0xf
	v_fmac_f32_dpp v55, v130, v70 quad_perm:[1,1,1,1] row_mask:0xf bank_mask:0xf
	v_fmac_f32_dpp v63, v99, v71 quad_perm:[1,1,1,1] row_mask:0xf bank_mask:0xf
	v_fmac_f32_dpp v62, v103, v71 quad_perm:[1,1,1,1] row_mask:0xf bank_mask:0xf
	v_fmac_f32_dpp v61, v107, v71 quad_perm:[1,1,1,1] row_mask:0xf bank_mask:0xf
	v_fmac_f32_dpp v60, v111, v71 quad_perm:[1,1,1,1] row_mask:0xf bank_mask:0xf
	v_fmac_f32_dpp v59, v115, v71 quad_perm:[1,1,1,1] row_mask:0xf bank_mask:0xf
	v_fmac_f32_dpp v58, v119, v71 quad_perm:[1,1,1,1] row_mask:0xf bank_mask:0xf
	v_fmac_f32_dpp v57, v123, v71 quad_perm:[1,1,1,1] row_mask:0xf bank_mask:0xf
	v_fmac_f32_dpp v56, v127, v71 quad_perm:[1,1,1,1] row_mask:0xf bank_mask:0xf
	v_fmac_f32_dpp v55, v131, v71 quad_perm:[1,1,1,1] row_mask:0xf bank_mask:0xf
; #define LAS __attribute__((address_space(3)))
; __device__ __forceinline__ void adaln_unit(const Args& a, LAS unsigned char* lds, int unit, int tid, int wave, int lane) {
;     ...
;         for (int k = 0; k < 128; k += 16) {
;             float w[16];
; #pragma unroll
;             for (int e = 0; e < 16; ++e) w[e] = W[(size_t)(kh * 1024 + kb + k + e) * N + jc];
; #pragma unroll
;             for (int q = 0; q < 4; ++q)
; #pragma unroll
;                 for (int r = 0; r < 18; ++r) { const f32x4 s = *(const LAS f32x4*)(sc + r * 1024 + kb + k + 4 * q); acc[r] += s[0] * w[4 * q] + s[1] * w[4 * q + 1] + s[2] * w[4 * q + 2] + s[3] * w[4 * q + 3]; }
	v_fmac_f32_dpp v63, v96, v72 quad_perm:[2,2,2,2] row_mask:0xf bank_mask:0xf
	v_fmac_f32_dpp v62, v100, v72 quad_perm:[2,2,2,2] row_mask:0xf bank_mask:0xf
	v_fmac_f32_dpp v61, v104, v72 quad_perm:[2,2,2,2] row_mask:0xf bank_mask:0xf
	v_fmac_f32_dpp v60, v108, v72 quad_perm:[2,2,2,2] row_mask:0xf bank_mask:0xf
	v_fmac_f32_dpp v59, v112, v72 quad_perm:[2,2,2,2] row_mask:0xf bank_mask:0xf
	v_fmac_f32_dpp v58, v116, v72 quad_perm:[2,2,2,2] row_mask:0xf bank_mask:0xf
	v_fmac_f32_dpp v57, v120, v72 quad_perm:[2,2,2,2] row_mask:0xf bank_mask:0xf
	v_fmac_f32_dpp v56, v124, v72 quad_perm:[2,2,2,2] row_mask:0xf bank_mask:0xf
	v_fmac_f32_dpp v55, v128, v72 quad_perm:[2,2,2,2] row_mask:0xf bank_mask:0xf
	v_fmac_f32_dpp v63, v97, v73 quad_perm:[2,2,2,2] row_mask:0xf bank_mask:0xf
	v_fmac_f32_dpp v62, v101, v73 quad_perm:[2,2,2,2] row_mask:0xf bank_mask:0xf
	v_fmac_f32_dpp v61, v105, v73 quad_perm:[2,2,2,2] row_mask:0xf bank_mask:0xf
	v_fmac_f32_dpp v60, v109, v73 quad_perm:[2,2,2,2] row_mask:0xf bank_mask:0xf
	v_fmac_f32_dpp v59, v113, v73 quad_perm:[2,2,2,2] row_mask:0xf bank_mask:0xf
	v_fmac_f32_dpp v58, v117, v73 quad_perm:[2,2,2,2] row_mask:0xf bank_mask:0xf
	v_fmac_f32_dpp v57, v121, v73 quad_perm:[2,2,2,2] row_mask:0xf bank_mask:0xf
	v_fmac_f32_dpp v56, v125, v73 quad_perm:[2,2,2,2] row_mask:0xf bank_mask:0xf
	v_fmac_f32_dpp v55, v129, v73 quad_perm:[2,2,2,2] row_mask:0xf bank_mask:0xf
	v_fmac_f32_dpp v63, v98, v74 quad_perm:[2,2,2,2] row_mask:0xf bank_mask:0xf
	v_fmac_f32_dpp v62, v102, v74 quad_perm:[2,2,2,2] row_mask:0xf bank_mask:0xf
	v_fmac_f32_dpp v61, v106, v74 quad_perm:[2,2,2,2] row_mask:0xf bank_mask:0xf
	v_fmac_f32_dpp v60, v110, v74 quad_perm:[2,2,2,2] row_mask:0xf bank_mask:0xf
	v_fmac_f32_dpp v59, v114, v74 quad_perm:[2,2,2,2] row_mask:0xf bank_mask:0xf
	v_fmac_f32_dpp v58, v118, v74 quad_perm:[2,2,2,2] row_mask:0xf bank_mask:0xf
	v_fmac_f32_dpp v57, v122, v74 quad_perm:[2,2,2,2] row_mask:0xf bank_mask:0xf
	v_fmac_f32_dpp v56, v126, v74 quad_perm:[2,2,2,2] row_mask:0xf bank_mask:0xf
	v_fmac_f32_dpp v55, v130, v74 quad_perm:[2,2,2,2] row_mask:0xf bank_mask:0xf
	v_fmac_f32_dpp v63, v99, v75 quad_perm:[2,2,2,2] row_mask:0xf bank_mask:0xf
	v_fmac_f32_dpp v62, v103, v75 quad_perm:[2,2,2,2] row_mask:0xf bank_mask:0xf
	v_fmac_f32_dpp v61, v107, v75 quad_perm:[2,2,2,2] row_mask:0xf bank_mask:0xf
	v_fmac_f32_dpp v60, v111, v75 quad_perm:[2,2,2,2] row_mask:0xf bank_mask:0xf
	v_fmac_f32_dpp v59, v115, v75 quad_perm:[2,2,2,2] row_mask:0xf bank_mask:0xf
	v_fmac_f32_dpp v58, v119, v75 quad_perm:[2,2,2,2] row_mask:0xf bank_mask:0xf
	v_fmac_f32_dpp v57, v123, v75 quad_perm:[2,2,2,2] row_mask:0xf bank_mask:0xf
	v_fmac_f32_dpp v56, v127, v75 quad_perm:[2,2,2,2] row_mask:0xf bank_mask:0xf
	v_fmac_f32_dpp v55, v131, v75 quad_perm:[2,2,2,2] row_mask:0xf bank_mask:0xf
	v_fmac_f32_dpp v63, v96, v76 quad_perm:[3,3,3,3] row_mask:0xf bank_mask:0xf
	v_fmac_f32_dpp v62, v100, v76 quad_perm:[3,3,3,3] row_mask:0xf bank_mask:0xf
	v_fmac_f32_dpp v61, v104, v76 quad_perm:[3,3,3,3] row_mask:0xf bank_mask:0xf
	v_fmac_f32_dpp v60, v108, v76 quad_perm:[3,3,3,3] row_mask:0xf bank_mask:0xf
	v_fmac_f32_dpp v59, v112, v76 quad_perm:[3,3,3,3] row_mask:0xf bank_mask:0xf
	v_fmac_f32_dpp v58, v116, v76 quad_perm:[3,3,3,3] row_mask:0xf bank_mask:0xf
	v_fmac_f32_dpp v57, v120, v76 quad_perm:[3,3,3,3] row_mask:0xf bank_mask:0xf
	v_fmac_f32_dpp v56, v124, v76 quad_perm:[3,3,3,3] row_mask:0xf bank_mask:0xf
	v_fmac_f32_dpp v55, v128, v76 quad_perm:[3,3,3,3] row_mask:0xf bank_mask:0xf
	v_fmac_f32_dpp v63, v97, v77 quad_perm:[3,3,3,3] row_mask:0xf bank_mask:0xf
	v_fmac_f32_dpp v62, v101, v77 quad_perm:[3,3,3,3] row_mask:0xf bank_mask:0xf
	v_fmac_f32_dpp v61, v105, v77 quad_perm:[3,3,3,3] row_mask:0xf bank_mask:0xf
	v_fmac_f32_dpp v60, v109, v77 quad_perm:[3,3,3,3] row_mask:0xf bank_mask:0xf
	v_fmac_f32_dpp v59, v113, v77 quad_perm:[3,3,3,3] row_mask:0xf bank_mask:0xf
	v_fmac_f32_dpp v58, v117, v77 quad_perm:[3,3,3,3] row_mask:0xf bank_mask:0xf
	v_fmac_f32_dpp v57, v121, v77 quad_perm:[3,3,3,3] row_mask:0xf bank_mask:0xf
	v_fmac_f32_dpp v56, v125, v77 quad_perm:[3,3,3,3] row_mask:0xf bank_mask:0xf
	v_fmac_f32_dpp v55, v129, v77 quad_perm:[3,3,3,3] row_mask:0xf bank_mask:0xf
	v_fmac_f32_dpp v63, v98, v78 quad_perm:[3,3,3,3] row_mask:0xf bank_mask:0xf
	v_fmac_f32_dpp v62, v102, v78 quad_perm:[3,3,3,3] row_mask:0xf bank_mask:0xf
	v_fmac_f32_dpp v61, v106, v78 quad_perm:[3,3,3,3] row_mask:0xf bank_mask:0xf
	v_fmac_f32_dpp v60, v110, v78 quad_perm:[3,3,3,3] row_mask:0xf bank_mask:0xf
	v_fmac_f32_dpp v59, v114, v78 quad_perm:[3,3,3,3] row_mask:0xf bank_mask:0xf
	v_fmac_f32_dpp v58, v118, v78 quad_perm:[3,3,3,3] row_mask:0xf bank_mask:0xf
	v_fmac_f32_dpp v57, v122, v78 quad_perm:[3,3,3,3] row_mask:0xf bank_mask:0xf
	v_fmac_f32_dpp v56, v126, v78 quad_perm:[3,3,3,3] row_mask:0xf bank_mask:0xf
	v_fmac_f32_dpp v55, v130, v78 quad_perm:[3,3,3,3] row_mask:0xf bank_mask:0xf
	v_fmac_f32_dpp v63, v99, v79 quad_perm:[3,3,3,3] row_mask:0xf bank_mask:0xf
	v_fmac_f32_dpp v62, v103, v79 quad_perm:[3,3,3,3] row_mask:0xf bank_mask:0xf
	v_fmac_f32_dpp v61, v107, v79 quad_perm:[3,3,3,3] row_mask:0xf bank_mask:0xf
	v_fmac_f32_dpp v60, v111, v79 quad_perm:[3,3,3,3] row_mask:0xf bank_mask:0xf
	v_fmac_f32_dpp v59, v115, v79 quad_perm:[3,3,3,3] row_mask:0xf bank_mask:0xf
	v_fmac_f32_dpp v58, v119, v79 quad_perm:[3,3,3,3] row_mask:0xf bank_mask:0xf
	v_fmac_f32_dpp v57, v123, v79 quad_perm:[3,3,3,3] row_mask:0xf bank_mask:0xf
	v_fmac_f32_dpp v56, v127, v79 quad_perm:[3,3,3,3] row_mask:0xf bank_mask:0xf
	v_fmac_f32_dpp v55, v131, v79 quad_perm:[3,3,3,3] row_mask:0xf bank_mask:0xf
	ds_read_b128 v[96:99], v133 offset:64
	ds_read_b128 v[100:103], v133 offset:4160
	ds_read_b128 v[104:107], v133 offset:8256
	ds_read_b128 v[108:111], v133 offset:12352
	ds_read_b128 v[112:115], v133 offset:16448
	ds_read_b128 v[116:119], v133 offset:20544
	ds_read_b128 v[120:123], v133 offset:24640
	ds_read_b128 v[124:127], v133 offset:28736
	ds_read_b128 v[128:131], v133 offset:32832
	s_waitcnt lgkmcnt(9)
; #define LAS __attribute__((address_space(3)))
; __device__ __forceinline__ void adaln_unit(const Args& a, LAS unsigned char* lds, int unit, int tid, int wave, int lane) {
;     ...
;         for (int k = 0; k < 128; k += 16) {
;             float w[16];
; #pragma unroll
;             for (int e = 0; e < 16; ++e) w[e] = W[(size_t)(kh * 1024 + kb + k + e) * N + jc];
; #pragma unroll
;             for (int q = 0; q < 4; ++q)
; #pragma unroll
;                 for (int r = 0; r < 18; ++r) { const f32x4 s = *(const LAS f32x4*)(sc + r * 1024 + kb + k + 4 * q); acc[r] += s[0] * w[4 * q] + s[1] * w[4 * q + 1] + s[2] * w[4 * q + 2] + s[3] * w[4 * q + 3]; }
	v_fmac_f32_dpp v54, v2, v64 quad_perm:[0,0,0,0] row_mask:0xf bank_mask:0xf
	v_fmac_f32_dpp v53, v6, v64 quad_perm:[0,0,0,0] row_mask:0xf bank_mask:0xf
	v_fmac_f32_dpp v52, v10, v64 quad_perm:[0,0,0,0] row_mask:0xf bank_mask:0xf
	v_fmac_f32_dpp v51, v14, v64 quad_perm:[0,0,0,0] row_mask:0xf bank_mask:0xf
	v_fmac_f32_dpp v50, v18, v64 quad_perm:[0,0,0,0] row_mask:0xf bank_mask:0xf
	v_fmac_f32_dpp v49, v22, v64 quad_perm:[0,0,0,0] row_mask:0xf bank_mask:0xf
	v_fmac_f32_dpp v48, v26, v64 quad_perm:[0,0,0,0] row_mask:0xf bank_mask:0xf
	v_fmac_f32_dpp v47, v30, v64 quad_perm:[0,0,0,0] row_mask:0xf bank_mask:0xf
	v_fmac_f32_dpp v46, v34, v64 quad_perm:[0,0,0,0] row_mask:0xf bank_mask:0xf
	v_fmac_f32_dpp v54, v3, v65 quad_perm:[0,0,0,0] row_mask:0xf bank_mask:0xf
	v_fmac_f32_dpp v53, v7, v65 quad_perm:[0,0,0,0] row_mask:0xf bank_mask:0xf
	v_fmac_f32_dpp v52, v11, v65 quad_perm:[0,0,0,0] row_mask:0xf bank_mask:0xf
	v_fmac_f32_dpp v51, v15, v65 quad_perm:[0,0,0,0] row_mask:0xf bank_mask:0xf
	v_fmac_f32_dpp v50, v19, v65 quad_perm:[0,0,0,0] row_mask:0xf bank_mask:0xf
	v_fmac_f32_dpp v49, v23, v65 quad_perm:[0,0,0,0] row_mask:0xf bank_mask:0xf
	v_fmac_f32_dpp v48, v27, v65 quad_perm:[0,0,0,0] row_mask:0xf bank_mask:0xf
	v_fmac_f32_dpp v47, v31, v65 quad_perm:[0,0,0,0] row_mask:0xf bank_mask:0xf
	v_fmac_f32_dpp v46, v35, v65 quad_perm:[0,0,0,0] row_mask:0xf bank_mask:0xf
	v_fmac_f32_dpp v54, v4, v66 quad_perm:[0,0,0,0] row_mask:0xf bank_mask:0xf
	v_fmac_f32_dpp v53, v8, v66 quad_perm:[0,0,0,0] row_mask:0xf bank_mask:0xf
	v_fmac_f32_dpp v52, v12, v66 quad_perm:[0,0,0,0] row_mask:0xf bank_mask:0xf
	v_fmac_f32_dpp v51, v16, v66 quad_perm:[0,0,0,0] row_mask:0xf bank_mask:0xf
	v_fmac_f32_dpp v50, v20, v66 quad_perm:[0,0,0,0] row_mask:0xf bank_mask:0xf
	v_fmac_f32_dpp v49, v24, v66 quad_perm:[0,0,0,0] row_mask:0xf bank_mask:0xf
	v_fmac_f32_dpp v48, v28, v66 quad_perm:[0,0,0,0] row_mask:0xf bank_mask:0xf
	v_fmac_f32_dpp v47, v32, v66 quad_perm:[0,0,0,0] row_mask:0xf bank_mask:0xf
	v_fmac_f32_dpp v46, v36, v66 quad_perm:[0,0,0,0] row_mask:0xf bank_mask:0xf
	v_fmac_f32_dpp v54, v5, v67 quad_perm:[0,0,0,0] row_mask:0xf bank_mask:0xf
	v_fmac_f32_dpp v53, v9, v67 quad_perm:[0,0,0,0] row_mask:0xf bank_mask:0xf
	v_fmac_f32_dpp v52, v13, v67 quad_perm:[0,0,0,0] row_mask:0xf bank_mask:0xf
	v_fmac_f32_dpp v51, v17, v67 quad_perm:[0,0,0,0] row_mask:0xf bank_mask:0xf
	v_fmac_f32_dpp v50, v21, v67 quad_perm:[0,0,0,0] row_mask:0xf bank_mask:0xf
	v_fmac_f32_dpp v49, v25, v67 quad_perm:[0,0,0,0] row_mask:0xf bank_mask:0xf
	v_fmac_f32_dpp v48, v29, v67 quad_perm:[0,0,0,0] row_mask:0xf bank_mask:0xf
	v_fmac_f32_dpp v47, v33, v67 quad_perm:[0,0,0,0] row_mask:0xf bank_mask:0xf
	v_fmac_f32_dpp v46, v37, v67 quad_perm:[0,0,0,0] row_mask:0xf bank_mask:0xf
	v_fmac_f32_dpp v54, v2, v68 quad_perm:[1,1,1,1] row_mask:0xf bank_mask:0xf
	v_fmac_f32_dpp v53, v6, v68 quad_perm:[1,1,1,1] row_mask:0xf bank_mask:0xf
	v_fmac_f32_dpp v52, v10, v68 quad_perm:[1,1,1,1] row_mask:0xf bank_mask:0xf
	v_fmac_f32_dpp v51, v14, v68 quad_perm:[1,1,1,1] row_mask:0xf bank_mask:0xf
	v_fmac_f32_dpp v50, v18, v68 quad_perm:[1,1,1,1] row_mask:0xf bank_mask:0xf
	v_fmac_f32_dpp v49, v22, v68 quad_perm:[1,1,1,1] row_mask:0xf bank_mask:0xf
	v_fmac_f32_dpp v48, v26, v68 quad_perm:[1,1,1,1] row_mask:0xf bank_mask:0xf
	v_fmac_f32_dpp v47, v30, v68 quad_perm:[1,1,1,1] row_mask:0xf bank_mask:0xf
	v_fmac_f32_dpp v46, v34, v68 quad_perm:[1,1,1,1] row_mask:0xf bank_mask:0xf
	v_fmac_f32_dpp v54, v3, v69 quad_perm:[1,1,1,1] row_mask:0xf bank_mask:0xf
	v_fmac_f32_dpp v53, v7, v69 quad_perm:[1,1,1,1] row_mask:0xf bank_mask:0xf
	v_fmac_f32_dpp v52, v11, v69 quad_perm:[1,1,1,1] row_mask:0xf bank_mask:0xf
	v_fmac_f32_dpp v51, v15, v69 quad_perm:[1,1,1,1] row_mask:0xf bank_mask:0xf
	v_fmac_f32_dpp v50, v19, v69 quad_perm:[1,1,1,1] row_mask:0xf bank_mask:0xf
	v_fmac_f32_dpp v49, v23, v69 quad_perm:[1,1,1,1] row_mask:0xf bank_mask:0xf
	v_fmac_f32_dpp v48, v27, v69 quad_perm:[1,1,1,1] row_mask:0xf bank_mask:0xf
	v_fmac_f32_dpp v47, v31, v69 quad_perm:[1,1,1,1] row_mask:0xf bank_mask:0xf
	v_fmac_f32_dpp v46, v35, v69 quad_perm:[1,1,1,1] row_mask:0xf bank_mask:0xf
	v_fmac_f32_dpp v54, v4, v70 quad_perm:[1,1,1,1] row_mask:0xf bank_mask:0xf
	v_fmac_f32_dpp v53, v8, v70 quad_perm:[1,1,1,1] row_mask:0xf bank_mask:0xf
	v_fmac_f32_dpp v52, v12, v70 quad_perm:[1,1,1,1] row_mask:0xf bank_mask:0xf
	v_fmac_f32_dpp v51, v16, v70 quad_perm:[1,1,1,1] row_mask:0xf bank_mask:0xf
	v_fmac_f32_dpp v50, v20, v70 quad_perm:[1,1,1,1] row_mask:0xf bank_mask:0xf
	v_fmac_f32_dpp v49, v24, v70 quad_perm:[1,1,1,1] row_mask:0xf bank_mask:0xf
	v_fmac_f32_dpp v48, v28, v70 quad_perm:[1,1,1,1] row_mask:0xf bank_mask:0xf
	v_fmac_f32_dpp v47, v32, v70 quad_perm:[1,1,1,1] row_mask:0xf bank_mask:0xf
	v_fmac_f32_dpp v46, v36, v70 quad_perm:[1,1,1,1] row_mask:0xf bank_mask:0xf
	v_fmac_f32_dpp v54, v5, v71 quad_perm:[1,1,1,1] row_mask:0xf bank_mask:0xf
	v_fmac_f32_dpp v53, v9, v71 quad_perm:[1,1,1,1] row_mask:0xf bank_mask:0xf
	v_fmac_f32_dpp v52, v13, v71 quad_perm:[1,1,1,1] row_mask:0xf bank_mask:0xf
	v_fmac_f32_dpp v51, v17, v71 quad_perm:[1,1,1,1] row_mask:0xf bank_mask:0xf
	v_fmac_f32_dpp v50, v21, v71 quad_perm:[1,1,1,1] row_mask:0xf bank_mask:0xf
	v_fmac_f32_dpp v49, v25, v71 quad_perm:[1,1,1,1] row_mask:0xf bank_mask:0xf
	v_fmac_f32_dpp v48, v29, v71 quad_perm:[1,1,1,1] row_mask:0xf bank_mask:0xf
	v_fmac_f32_dpp v47, v33, v71 quad_perm:[1,1,1,1] row_mask:0xf bank_mask:0xf
	v_fmac_f32_dpp v46, v37, v71 quad_perm:[1,1,1,1] row_mask:0xf bank_mask:0xf
	v_fmac_f32_dpp v54, v2, v72 quad_perm:[2,2,2,2] row_mask:0xf bank_mask:0xf
; #define LAS __attribute__((address_space(3)))
; __device__ __forceinline__ void adaln_unit(const Args& a, LAS unsigned char* lds, int unit, int tid, int wave, int lane) {
;     ...
;         for (int k = 0; k < 128; k += 16) {
;             float w[16];
; #pragma unroll
;             for (int e = 0; e < 16; ++e) w[e] = W[(size_t)(kh * 1024 + kb + k + e) * N + jc];
; #pragma unroll
;             for (int q = 0; q < 4; ++q)
; #pragma unroll
;                 for (int r = 0; r < 18; ++r) { const f32x4 s = *(const LAS f32x4*)(sc + r * 1024 + kb + k + 4 * q); acc[r] += s[0] * w[4 * q] + s[1] * w[4 * q + 1] + s[2] * w[4 * q + 2] + s[3] * w[4 * q + 3]; }
	v_fmac_f32_dpp v53, v6, v72 quad_perm:[2,2,2,2] row_mask:0xf bank_mask:0xf
	v_fmac_f32_dpp v52, v10, v72 quad_perm:[2,2,2,2] row_mask:0xf bank_mask:0xf
	v_fmac_f32_dpp v51, v14, v72 quad_perm:[2,2,2,2] row_mask:0xf bank_mask:0xf
	v_fmac_f32_dpp v50, v18, v72 quad_perm:[2,2,2,2] row_mask:0xf bank_mask:0xf
	v_fmac_f32_dpp v49, v22, v72 quad_perm:[2,2,2,2] row_mask:0xf bank_mask:0xf
	v_fmac_f32_dpp v48, v26, v72 quad_perm:[2,2,2,2] row_mask:0xf bank_mask:0xf
	v_fmac_f32_dpp v47, v30, v72 quad_perm:[2,2,2,2] row_mask:0xf bank_mask:0xf
	v_fmac_f32_dpp v46, v34, v72 quad_perm:[2,2,2,2] row_mask:0xf bank_mask:0xf
	v_fmac_f32_dpp v54, v3, v73 quad_perm:[2,2,2,2] row_mask:0xf bank_mask:0xf
	v_fmac_f32_dpp v53, v7, v73 quad_perm:[2,2,2,2] row_mask:0xf bank_mask:0xf
	v_fmac_f32_dpp v52, v11, v73 quad_perm:[2,2,2,2] row_mask:0xf bank_mask:0xf
	v_fmac_f32_dpp v51, v15, v73 quad_perm:[2,2,2,2] row_mask:0xf bank_mask:0xf
	v_fmac_f32_dpp v50, v19, v73 quad_perm:[2,2,2,2] row_mask:0xf bank_mask:0xf
	v_fmac_f32_dpp v49, v23, v73 quad_perm:[2,2,2,2] row_mask:0xf bank_mask:0xf
	v_fmac_f32_dpp v48, v27, v73 quad_perm:[2,2,2,2] row_mask:0xf bank_mask:0xf
	v_fmac_f32_dpp v47, v31, v73 quad_perm:[2,2,2,2] row_mask:0xf bank_mask:0xf
	v_fmac_f32_dpp v46, v35, v73 quad_perm:[2,2,2,2] row_mask:0xf bank_mask:0xf
	v_fmac_f32_dpp v54, v4, v74 quad_perm:[2,2,2,2] row_mask:0xf bank_mask:0xf
	v_fmac_f32_dpp v53, v8, v74 quad_perm:[2,2,2,2] row_mask:0xf bank_mask:0xf
	v_fmac_f32_dpp v52, v12, v74 quad_perm:[2,2,2,2] row_mask:0xf bank_mask:0xf
	v_fmac_f32_dpp v51, v16, v74 quad_perm:[2,2,2,2] row_mask:0xf bank_mask:0xf
	v_fmac_f32_dpp v50, v20, v74 quad_perm:[2,2,2,2] row_mask:0xf bank_mask:0xf
	v_fmac_f32_dpp v49, v24, v74 quad_perm:[2,2,2,2] row_mask:0xf bank_mask:0xf
	v_fmac_f32_dpp v48, v28, v74 quad_perm:[2,2,2,2] row_mask:0xf bank_mask:0xf
	v_fmac_f32_dpp v47, v32, v74 quad_perm:[2,2,2,2] row_mask:0xf bank_mask:0xf
	v_fmac_f32_dpp v46, v36, v74 quad_perm:[2,2,2,2] row_mask:0xf bank_mask:0xf
	v_fmac_f32_dpp v54, v5, v75 quad_perm:[2,2,2,2] row_mask:0xf bank_mask:0xf
	v_fmac_f32_dpp v53, v9, v75 quad_perm:[2,2,2,2] row_mask:0xf bank_mask:0xf
	v_fmac_f32_dpp v52, v13, v75 quad_perm:[2,2,2,2] row_mask:0xf bank_mask:0xf
	v_fmac_f32_dpp v51, v17, v75 quad_perm:[2,2,2,2] row_mask:0xf bank_mask:0xf
	v_fmac_f32_dpp v50, v21, v75 quad_perm:[2,2,2,2] row_mask:0xf bank_mask:0xf
	v_fmac_f32_dpp v49, v25, v75 quad_perm:[2,2,2,2] row_mask:0xf bank_mask:0xf
	v_fmac_f32_dpp v48, v29, v75 quad_perm:[2,2,2,2] row_mask:0xf bank_mask:0xf
	v_fmac_f32_dpp v47, v33, v75 quad_perm:[2,2,2,2] row_mask:0xf bank_mask:0xf
	v_fmac_f32_dpp v46, v37, v75 quad_perm:[2,2,2,2] row_mask:0xf bank_mask:0xf
	v_fmac_f32_dpp v54, v2, v76 quad_perm:[3,3,3,3] row_mask:0xf bank_mask:0xf
	v_fmac_f32_dpp v53, v6, v76 quad_perm:[3,3,3,3] row_mask:0xf bank_mask:0xf
	v_fmac_f32_dpp v52, v10, v76 quad_perm:[3,3,3,3] row_mask:0xf bank_mask:0xf
	v_fmac_f32_dpp v51, v14, v76 quad_perm:[3,3,3,3] row_mask:0xf bank_mask:0xf
	v_fmac_f32_dpp v50, v18, v76 quad_perm:[3,3,3,3] row_mask:0xf bank_mask:0xf
	v_fmac_f32_dpp v49, v22, v76 quad_perm:[3,3,3,3] row_mask:0xf bank_mask:0xf
	v_fmac_f32_dpp v48, v26, v76 quad_perm:[3,3,3,3] row_mask:0xf bank_mask:0xf
	v_fmac_f32_dpp v47, v30, v76 quad_perm:[3,3,3,3] row_mask:0xf bank_mask:0xf
	v_fmac_f32_dpp v46, v34, v76 quad_perm:[3,3,3,3] row_mask:0xf bank_mask:0xf
	v_fmac_f32_dpp v54, v3, v77 quad_perm:[3,3,3,3] row_mask:0xf bank_mask:0xf
	v_fmac_f32_dpp v53, v7, v77 quad_perm:[3,3,3,3] row_mask:0xf bank_mask:0xf
	v_fmac_f32_dpp v52, v11, v77 quad_perm:[3,3,3,3] row_mask:0xf bank_mask:0xf
	v_fmac_f32_dpp v51, v15, v77 quad_perm:[3,3,3,3] row_mask:0xf bank_mask:0xf
	v_fmac_f32_dpp v50, v19, v77 quad_perm:[3,3,3,3] row_mask:0xf bank_mask:0xf
	v_fmac_f32_dpp v49, v23, v77 quad_perm:[3,3,3,3] row_mask:0xf bank_mask:0xf
	v_fmac_f32_dpp v48, v27, v77 quad_perm:[3,3,3,3] row_mask:0xf bank_mask:0xf
	v_fmac_f32_dpp v47, v31, v77 quad_perm:[3,3,3,3] row_mask:0xf bank_mask:0xf
	v_fmac_f32_dpp v46, v35, v77 quad_perm:[3,3,3,3] row_mask:0xf bank_mask:0xf
	v_fmac_f32_dpp v54, v4, v78 quad_perm:[3,3,3,3] row_mask:0xf bank_mask:0xf
	v_fmac_f32_dpp v53, v8, v78 quad_perm:[3,3,3,3] row_mask:0xf bank_mask:0xf
	v_fmac_f32_dpp v52, v12, v78 quad_perm:[3,3,3,3] row_mask:0xf bank_mask:0xf
	v_fmac_f32_dpp v51, v16, v78 quad_perm:[3,3,3,3] row_mask:0xf bank_mask:0xf
	v_fmac_f32_dpp v50, v20, v78 quad_perm:[3,3,3,3] row_mask:0xf bank_mask:0xf
	v_fmac_f32_dpp v49, v24, v78 quad_perm:[3,3,3,3] row_mask:0xf bank_mask:0xf
	v_fmac_f32_dpp v48, v28, v78 quad_perm:[3,3,3,3] row_mask:0xf bank_mask:0xf
	v_fmac_f32_dpp v47, v32, v78 quad_perm:[3,3,3,3] row_mask:0xf bank_mask:0xf
	v_fmac_f32_dpp v46, v36, v78 quad_perm:[3,3,3,3] row_mask:0xf bank_mask:0xf
	v_fmac_f32_dpp v54, v5, v79 quad_perm:[3,3,3,3] row_mask:0xf bank_mask:0xf
	v_fmac_f32_dpp v53, v9, v79 quad_perm:[3,3,3,3] row_mask:0xf bank_mask:0xf
	v_fmac_f32_dpp v52, v13, v79 quad_perm:[3,3,3,3] row_mask:0xf bank_mask:0xf
	v_fmac_f32_dpp v51, v17, v79 quad_perm:[3,3,3,3] row_mask:0xf bank_mask:0xf
	v_fmac_f32_dpp v50, v21, v79 quad_perm:[3,3,3,3] row_mask:0xf bank_mask:0xf
	v_fmac_f32_dpp v49, v25, v79 quad_perm:[3,3,3,3] row_mask:0xf bank_mask:0xf
	v_fmac_f32_dpp v48, v29, v79 quad_perm:[3,3,3,3] row_mask:0xf bank_mask:0xf
	v_fmac_f32_dpp v47, v33, v79 quad_perm:[3,3,3,3] row_mask:0xf bank_mask:0xf
	v_fmac_f32_dpp v46, v37, v79 quad_perm:[3,3,3,3] row_mask:0xf bank_mask:0xf
	ds_read_b128 v[2:5], v133 offset:36928
	ds_read_b128 v[6:9], v133 offset:41024
	ds_read_b128 v[10:13], v133 offset:45120
	ds_read_b128 v[14:17], v133 offset:49216
	ds_read_b128 v[18:21], v133 offset:53312
	ds_read_b128 v[22:25], v133 offset:57408
	ds_read_b128 v[26:29], v133 offset:61504
	ds_read_b128 v[30:33], v134 offset:64
	ds_read_b128 v[34:37], v134 offset:4160
	s_cmp_eq_u32 s82, 3
	s_cbranch_scc1 .Lada_last
; __device__ __forceinline__ void adaln_unit(const Args& a, LAS unsigned char* lds, int unit, int tid, int wave, int lane) {
;     ...
;         for (int k = 0; k < 128; k += 16) {
;             float w[16];
; #pragma unroll
;             for (int e = 0; e < 16; ++e) w[e] = W[(size_t)(kh * 1024 + kb + k + e) * N + jc];
	global_load_dword v64, v132, s[84:85]
	s_add_u32 s84, s84, s74
	s_addc_u32 s85, s85, s75
	global_load_dword v65, v132, s[84:85]
	s_add_u32 s84, s84, s74
	s_addc_u32 s85, s85, s75
	global_load_dword v66, v132, s[84:85]
	s_add_u32 s84, s84, s74
	s_addc_u32 s85, s85, s75
	global_load_dword v67, v132, s[84:85]
	s_add_u32 s84, s84, s74
	s_addc_u32 s85, s85, s75
	global_load_dword v68, v132, s[84:85]
	s_add_u32 s84, s84, s74
	s_addc_u32 s85, s85, s75
	global_load_dword v69, v132, s[84:85]
	s_add_u32 s84, s84, s74
	s_addc_u32 s85, s85, s75
	global_load_dword v70, v132, s[84:85]
	s_add_u32 s84, s84, s74
	s_addc_u32 s85, s85, s75
	global_load_dword v71, v132, s[84:85]
	s_add_u32 s84, s84, s74
	s_addc_u32 s85, s85, s75
	global_load_dword v72, v132, s[84:85]
	s_add_u32 s84, s84, s74
	s_addc_u32 s85, s85, s75
	global_load_dword v73, v132, s[84:85]
	s_add_u32 s84, s84, s74
	s_addc_u32 s85, s85, s75
	global_load_dword v74, v132, s[84:85]
	s_add_u32 s84, s84, s74
	s_addc_u32 s85, s85, s75
	global_load_dword v75, v132, s[84:85]
	s_add_u32 s84, s84, s74
	s_addc_u32 s85, s85, s75
	global_load_dword v76, v132, s[84:85]
	s_add_u32 s84, s84, s74
	s_addc_u32 s85, s85, s75
	global_load_dword v77, v132, s[84:85]
	s_add_u32 s84, s84, s74
	s_addc_u32 s85, s85, s75
	global_load_dword v78, v132, s[84:85]
	s_add_u32 s84, s84, s74
	s_addc_u32 s85, s85, s75
	global_load_dword v79, v132, s[84:85]
	s_add_u32 s84, s84, s74
	s_addc_u32 s85, s85, s75
	s_waitcnt vmcnt(16)
	s_branch .Lada_h1

; #define LAS __attribute__((address_space(3)))
; __device__ __forceinline__ void adaln_unit(const Args& a, LAS unsigned char* lds, int unit, int tid, int wave, int lane) {
;     ...
;         for (int k = 0; k < 128; k += 16) {
;             float w[16];
; #pragma unroll
;             for (int e = 0; e < 16; ++e) w[e] = W[(size_t)(kh * 1024 + kb + k + e) * N + jc];
; #pragma unroll
;             for (int q = 0; q < 4; ++q)
; #pragma unroll
;                 for (int r = 0; r < 18; ++r) { const f32x4 s = *(const LAS f32x4*)(sc + r * 1024 + kb + k + 4 * q); acc[r] += s[0] * w[4 * q] + s[1] * w[4 * q + 1] + s[2] * w[4 * q + 2] + s[3] * w[4 * q + 3]; }
.Lada_h1:
	s_waitcnt lgkmcnt(9)
	v_fmac_f32_dpp v63, v96, v80 quad_perm:[0,0,0,0] row_mask:0xf bank_mask:0xf
	v_fmac_f32_dpp v62, v100, v80 quad_perm:[0,0,0,0] row_mask:0xf bank_mask:0xf
	v_fmac_f32_dpp v61, v104, v80 quad_perm:[0,0,0,0] row_mask:0xf bank_mask:0xf
	v_fmac_f32_dpp v60, v108, v80 quad_perm:[0,0,0,0] row_mask:0xf bank_mask:0xf
	v_fmac_f32_dpp v59, v112, v80 quad_perm:[0,0,0,0] row_mask:0xf bank_mask:0xf
	v_fmac_f32_dpp v58, v116, v80 quad_perm:[0,0,0,0] row_mask:0xf bank_mask:0xf
	v_fmac_f32_dpp v57, v120, v80 quad_perm:[0,0,0,0] row_mask:0xf bank_mask:0xf
	v_fmac_f32_dpp v56, v124, v80 quad_perm:[0,0,0,0] row_mask:0xf bank_mask:0xf
	v_fmac_f32_dpp v55, v128, v80 quad_perm:[0,0,0,0] row_mask:0xf bank_mask:0xf
	v_fmac_f32_dpp v63, v97, v81 quad_perm:[0,0,0,0] row_mask:0xf bank_mask:0xf
	v_fmac_f32_dpp v62, v101, v81 quad_perm:[0,0,0,0] row_mask:0xf bank_mask:0xf
	v_fmac_f32_dpp v61, v105, v81 quad_perm:[0,0,0,0] row_mask:0xf bank_mask:0xf
	v_fmac_f32_dpp v60, v109, v81 quad_perm:[0,0,0,0] row_mask:0xf bank_mask:0xf
	v_fmac_f32_dpp v59, v113, v81 quad_perm:[0,0,0,0] row_mask:0xf bank_mask:0xf
	v_fmac_f32_dpp v58, v117, v81 quad_perm:[0,0,0,0] row_mask:0xf bank_mask:0xf
	v_fmac_f32_dpp v57, v121, v81 quad_perm:[0,0,0,0] row_mask:0xf bank_mask:0xf
	v_fmac_f32_dpp v56, v125, v81 quad_perm:[0,0,0,0] row_mask:0xf bank_mask:0xf
	v_fmac_f32_dpp v55, v129, v81 quad_perm:[0,0,0,0] row_mask:0xf bank_mask:0xf
	v_fmac_f32_dpp v63, v98, v82 quad_perm:[0,0,0,0] row_mask:0xf bank_mask:0xf
	v_fmac_f32_dpp v62, v102, v82 quad_perm:[0,0,0,0] row_mask:0xf bank_mask:0xf
	v_fmac_f32_dpp v61, v106, v82 quad_perm:[0,0,0,0] row_mask:0xf bank_mask:0xf
	v_fmac_f32_dpp v60, v110, v82 quad_perm:[0,0,0,0] row_mask:0xf bank_mask:0xf
	v_fmac_f32_dpp v59, v114, v82 quad_perm:[0,0,0,0] row_mask:0xf bank_mask:0xf
	v_fmac_f32_dpp v58, v118, v82 quad_perm:[0,0,0,0] row_mask:0xf bank_mask:0xf
	v_fmac_f32_dpp v57, v122, v82 quad_perm:[0,0,0,0] row_mask:0xf bank_mask:0xf
	v_fmac_f32_dpp v56, v126, v82 quad_perm:[0,0,0,0] row_mask:0xf bank_mask:0xf
	v_fmac_f32_dpp v55, v130, v82 quad_perm:[0,0,0,0] row_mask:0xf bank_mask:0xf
	v_fmac_f32_dpp v63, v99, v83 quad_perm:[0,0,0,0] row_mask:0xf bank_mask:0xf
	v_fmac_f32_dpp v62, v103, v83 quad_perm:[0,0,0,0] row_mask:0xf bank_mask:0xf
	v_fmac_f32_dpp v61, v107, v83 quad_perm:[0,0,0,0] row_mask:0xf bank_mask:0xf
	v_fmac_f32_dpp v60, v111, v83 quad_perm:[0,0,0,0] row_mask:0xf bank_mask:0xf
	v_fmac_f32_dpp v59, v115, v83 quad_perm:[0,0,0,0] row_mask:0xf bank_mask:0xf
	v_fmac_f32_dpp v58, v119, v83 quad_perm:[0,0,0,0] row_mask:0xf bank_mask:0xf
	v_fmac_f32_dpp v57, v123, v83 quad_perm:[0,0,0,0] row_mask:0xf bank_mask:0xf
	v_fmac_f32_dpp v56, v127, v83 quad_perm:[0,0,0,0] row_mask:0xf bank_mask:0xf
	v_fmac_f32_dpp v55, v131, v83 quad_perm:[0,0,0,0] row_mask:0xf bank_mask:0xf
	v_fmac_f32_dpp v63, v96, v84 quad_perm:[1,1,1,1] row_mask:0xf bank_mask:0xf
	v_fmac_f32_dpp v62, v100, v84 quad_perm:[1,1,1,1] row_mask:0xf bank_mask:0xf
	v_fmac_f32_dpp v61, v104, v84 quad_perm:[1,1,1,1] row_mask:0xf bank_mask:0xf
	v_fmac_f32_dpp v60, v108, v84 quad_perm:[1,1,1,1] row_mask:0xf bank_mask:0xf
	v_fmac_f32_dpp v59, v112, v84 quad_perm:[1,1,1,1] row_mask:0xf bank_mask:0xf
	v_fmac_f32_dpp v58, v116, v84 quad_perm:[1,1,1,1] row_mask:0xf bank_mask:0xf
	v_fmac_f32_dpp v57, v120, v84 quad_perm:[1,1,1,1] row_mask:0xf bank_mask:0xf
	v_fmac_f32_dpp v56, v124, v84 quad_perm:[1,1,1,1] row_mask:0xf bank_mask:0xf
	v_fmac_f32_dpp v55, v128, v84 quad_perm:[1,1,1,1] row_mask:0xf bank_mask:0xf
	v_fmac_f32_dpp v63, v97, v85 quad_perm:[1,1,1,1] row_mask:0xf bank_mask:0xf
	v_fmac_f32_dpp v62, v101, v85 quad_perm:[1,1,1,1] row_mask:0xf bank_mask:0xf
	v_fmac_f32_dpp v61, v105, v85 quad_perm:[1,1,1,1] row_mask:0xf bank_mask:0xf
	v_fmac_f32_dpp v60, v109, v85 quad_perm:[1,1,1,1] row_mask:0xf bank_mask:0xf
	v_fmac_f32_dpp v59, v113, v85 quad_perm:[1,1,1,1] row_mask:0xf bank_mask:0xf
	v_fmac_f32_dpp v58, v117, v85 quad_perm:[1,1,1,1] row_mask:0xf bank_mask:0xf
	v_fmac_f32_dpp v57, v121, v85 quad_perm:[1,1,1,1] row_mask:0xf bank_mask:0xf
	v_fmac_f32_dpp v56, v125, v85 quad_perm:[1,1,1,1] row_mask:0xf bank_mask:0xf
	v_fmac_f32_dpp v55, v129, v85 quad_perm:[1,1,1,1] row_mask:0xf bank_mask:0xf
	v_fmac_f32_dpp v63, v98, v86 quad_perm:[1,1,1,1] row_mask:0xf bank_mask:0xf
	v_fmac_f32_dpp v62, v102, v86 quad_perm:[1,1,1,1] row_mask:0xf bank_mask:0xf
	v_fmac_f32_dpp v61, v106, v86 quad_perm:[1,1,1,1] row_mask:0xf bank_mask:0xf
	v_fmac_f32_dpp v60, v110, v86 quad_perm:[1,1,1,1] row_mask:0xf bank_mask:0xf
	v_fmac_f32_dpp v59, v114, v86 quad_perm:[1,1,1,1] row_mask:0xf bank_mask:0xf
	v_fmac_f32_dpp v58, v118, v86 quad_perm:[1,1,1,1] row_mask:0xf bank_mask:0xf
	v_fmac_f32_dpp v57, v122, v86 quad_perm:[1,1,1,1] row_mask:0xf bank_mask:0xf
	v_fmac_f32_dpp v56, v126, v86 quad_perm:[1,1,1,1] row_mask:0xf bank_mask:0xf
	v_fmac_f32_dpp v55, v130, v86 quad_perm:[1,1,1,1] row_mask:0xf bank_mask:0xf
	v_fmac_f32_dpp v63, v99, v87 quad_perm:[1,1,1,1] row_mask:0xf bank_mask:0xf
	v_fmac_f32_dpp v62, v103, v87 quad_perm:[1,1,1,1] row_mask:0xf bank_mask:0xf
	v_fmac_f32_dpp v61, v107, v87 quad_perm:[1,1,1,1] row_mask:0xf bank_mask:0xf
	v_fmac_f32_dpp v60, v111, v87 quad_perm:[1,1,1,1] row_mask:0xf bank_mask:0xf
	v_fmac_f32_dpp v59, v115, v87 quad_perm:[1,1,1,1] row_mask:0xf bank_mask:0xf
	v_fmac_f32_dpp v58, v119, v87 quad_perm:[1,1,1,1] row_mask:0xf bank_mask:0xf
	v_fmac_f32_dpp v57, v123, v87 quad_perm:[1,1,1,1] row_mask:0xf bank_mask:0xf
	v_fmac_f32_dpp v56, v127, v87 quad_perm:[1,1,1,1] row_mask:0xf bank_mask:0xf
	v_fmac_f32_dpp v55, v131, v87 quad_perm:[1,1,1,1] row_mask:0xf bank_mask:0xf
; #define LAS __attribute__((address_space(3)))
; __device__ __forceinline__ void adaln_unit(const Args& a, LAS unsigned char* lds, int unit, int tid, int wave, int lane) {
;     ...
;         for (int k = 0; k < 128; k += 16) {
;             float w[16];
; #pragma unroll
;             for (int e = 0; e < 16; ++e) w[e] = W[(size_t)(kh * 1024 + kb + k + e) * N + jc];
; #pragma unroll
;             for (int q = 0; q < 4; ++q)
; #pragma unroll
;                 for (int r = 0; r < 18; ++r) { const f32x4 s = *(const LAS f32x4*)(sc + r * 1024 + kb + k + 4 * q); acc[r] += s[0] * w[4 * q] + s[1] * w[4 * q + 1] + s[2] * w[4 * q + 2] + s[3] * w[4 * q + 3]; }
	v_fmac_f32_dpp v63, v96, v88 quad_perm:[2,2,2,2] row_mask:0xf bank_mask:0xf
	v_fmac_f32_dpp v62, v100, v88 quad_perm:[2,2,2,2] row_mask:0xf bank_mask:0xf
	v_fmac_f32_dpp v61, v104, v88 quad_perm:[2,2,2,2] row_mask:0xf bank_mask:0xf
	v_fmac_f32_dpp v60, v108, v88 quad_perm:[2,2,2,2] row_mask:0xf bank_mask:0xf
	v_fmac_f32_dpp v59, v112, v88 quad_perm:[2,2,2,2] row_mask:0xf bank_mask:0xf
	v_fmac_f32_dpp v58, v116, v88 quad_perm:[2,2,2,2] row_mask:0xf bank_mask:0xf
	v_fmac_f32_dpp v57, v120, v88 quad_perm:[2,2,2,2] row_mask:0xf bank_mask:0xf
	v_fmac_f32_dpp v56, v124, v88 quad_perm:[2,2,2,2] row_mask:0xf bank_mask:0xf
	v_fmac_f32_dpp v55, v128, v88 quad_perm:[2,2,2,2] row_mask:0xf bank_mask:0xf
	v_fmac_f32_dpp v63, v97, v89 quad_perm:[2,2,2,2] row_mask:0xf bank_mask:0xf
	v_fmac_f32_dpp v62, v101, v89 quad_perm:[2,2,2,2] row_mask:0xf bank_mask:0xf
	v_fmac_f32_dpp v61, v105, v89 quad_perm:[2,2,2,2] row_mask:0xf bank_mask:0xf
	v_fmac_f32_dpp v60, v109, v89 quad_perm:[2,2,2,2] row_mask:0xf bank_mask:0xf
	v_fmac_f32_dpp v59, v113, v89 quad_perm:[2,2,2,2] row_mask:0xf bank_mask:0xf
	v_fmac_f32_dpp v58, v117, v89 quad_perm:[2,2,2,2] row_mask:0xf bank_mask:0xf
	v_fmac_f32_dpp v57, v121, v89 quad_perm:[2,2,2,2] row_mask:0xf bank_mask:0xf
	v_fmac_f32_dpp v56, v125, v89 quad_perm:[2,2,2,2] row_mask:0xf bank_mask:0xf
	v_fmac_f32_dpp v55, v129, v89 quad_perm:[2,2,2,2] row_mask:0xf bank_mask:0xf
	v_fmac_f32_dpp v63, v98, v90 quad_perm:[2,2,2,2] row_mask:0xf bank_mask:0xf
	v_fmac_f32_dpp v62, v102, v90 quad_perm:[2,2,2,2] row_mask:0xf bank_mask:0xf
	v_fmac_f32_dpp v61, v106, v90 quad_perm:[2,2,2,2] row_mask:0xf bank_mask:0xf
	v_fmac_f32_dpp v60, v110, v90 quad_perm:[2,2,2,2] row_mask:0xf bank_mask:0xf
	v_fmac_f32_dpp v59, v114, v90 quad_perm:[2,2,2,2] row_mask:0xf bank_mask:0xf
	v_fmac_f32_dpp v58, v118, v90 quad_perm:[2,2,2,2] row_mask:0xf bank_mask:0xf
	v_fmac_f32_dpp v57, v122, v90 quad_perm:[2,2,2,2] row_mask:0xf bank_mask:0xf
	v_fmac_f32_dpp v56, v126, v90 quad_perm:[2,2,2,2] row_mask:0xf bank_mask:0xf
	v_fmac_f32_dpp v55, v130, v90 quad_perm:[2,2,2,2] row_mask:0xf bank_mask:0xf
	v_fmac_f32_dpp v63, v99, v91 quad_perm:[2,2,2,2] row_mask:0xf bank_mask:0xf
	v_fmac_f32_dpp v62, v103, v91 quad_perm:[2,2,2,2] row_mask:0xf bank_mask:0xf
	v_fmac_f32_dpp v61, v107, v91 quad_perm:[2,2,2,2] row_mask:0xf bank_mask:0xf
	v_fmac_f32_dpp v60, v111, v91 quad_perm:[2,2,2,2] row_mask:0xf bank_mask:0xf
	v_fmac_f32_dpp v59, v115, v91 quad_perm:[2,2,2,2] row_mask:0xf bank_mask:0xf
	v_fmac_f32_dpp v58, v119, v91 quad_perm:[2,2,2,2] row_mask:0xf bank_mask:0xf
	v_fmac_f32_dpp v57, v123, v91 quad_perm:[2,2,2,2] row_mask:0xf bank_mask:0xf
	v_fmac_f32_dpp v56, v127, v91 quad_perm:[2,2,2,2] row_mask:0xf bank_mask:0xf
	v_fmac_f32_dpp v55, v131, v91 quad_perm:[2,2,2,2] row_mask:0xf bank_mask:0xf
	v_fmac_f32_dpp v63, v96, v92 quad_perm:[3,3,3,3] row_mask:0xf bank_mask:0xf
	v_fmac_f32_dpp v62, v100, v92 quad_perm:[3,3,3,3] row_mask:0xf bank_mask:0xf
	v_fmac_f32_dpp v61, v104, v92 quad_perm:[3,3,3,3] row_mask:0xf bank_mask:0xf
	v_fmac_f32_dpp v60, v108, v92 quad_perm:[3,3,3,3] row_mask:0xf bank_mask:0xf
	v_fmac_f32_dpp v59, v112, v92 quad_perm:[3,3,3,3] row_mask:0xf bank_mask:0xf
	v_fmac_f32_dpp v58, v116, v92 quad_perm:[3,3,3,3] row_mask:0xf bank_mask:0xf
	v_fmac_f32_dpp v57, v120, v92 quad_perm:[3,3,3,3] row_mask:0xf bank_mask:0xf
	v_fmac_f32_dpp v56, v124, v92 quad_perm:[3,3,3,3] row_mask:0xf bank_mask:0xf
	v_fmac_f32_dpp v55, v128, v92 quad_perm:[3,3,3,3] row_mask:0xf bank_mask:0xf
	v_fmac_f32_dpp v63, v97, v93 quad_perm:[3,3,3,3] row_mask:0xf bank_mask:0xf
	v_fmac_f32_dpp v62, v101, v93 quad_perm:[3,3,3,3] row_mask:0xf bank_mask:0xf
	v_fmac_f32_dpp v61, v105, v93 quad_perm:[3,3,3,3] row_mask:0xf bank_mask:0xf
	v_fmac_f32_dpp v60, v109, v93 quad_perm:[3,3,3,3] row_mask:0xf bank_mask:0xf
	v_fmac_f32_dpp v59, v113, v93 quad_perm:[3,3,3,3] row_mask:0xf bank_mask:0xf
	v_fmac_f32_dpp v58, v117, v93 quad_perm:[3,3,3,3] row_mask:0xf bank_mask:0xf
	v_fmac_f32_dpp v57, v121, v93 quad_perm:[3,3,3,3] row_mask:0xf bank_mask:0xf
	v_fmac_f32_dpp v56, v125, v93 quad_perm:[3,3,3,3] row_mask:0xf bank_mask:0xf
	v_fmac_f32_dpp v55, v129, v93 quad_perm:[3,3,3,3] row_mask:0xf bank_mask:0xf
	v_fmac_f32_dpp v63, v98, v94 quad_perm:[3,3,3,3] row_mask:0xf bank_mask:0xf
	v_fmac_f32_dpp v62, v102, v94 quad_perm:[3,3,3,3] row_mask:0xf bank_mask:0xf
	v_fmac_f32_dpp v61, v106, v94 quad_perm:[3,3,3,3] row_mask:0xf bank_mask:0xf
	v_fmac_f32_dpp v60, v110, v94 quad_perm:[3,3,3,3] row_mask:0xf bank_mask:0xf
	v_fmac_f32_dpp v59, v114, v94 quad_perm:[3,3,3,3] row_mask:0xf bank_mask:0xf
	v_fmac_f32_dpp v58, v118, v94 quad_perm:[3,3,3,3] row_mask:0xf bank_mask:0xf
	v_fmac_f32_dpp v57, v122, v94 quad_perm:[3,3,3,3] row_mask:0xf bank_mask:0xf
	v_fmac_f32_dpp v56, v126, v94 quad_perm:[3,3,3,3] row_mask:0xf bank_mask:0xf
	v_fmac_f32_dpp v55, v130, v94 quad_perm:[3,3,3,3] row_mask:0xf bank_mask:0xf
	v_fmac_f32_dpp v63, v99, v95 quad_perm:[3,3,3,3] row_mask:0xf bank_mask:0xf
	v_fmac_f32_dpp v62, v103, v95 quad_perm:[3,3,3,3] row_mask:0xf bank_mask:0xf
	v_fmac_f32_dpp v61, v107, v95 quad_perm:[3,3,3,3] row_mask:0xf bank_mask:0xf
	v_fmac_f32_dpp v60, v111, v95 quad_perm:[3,3,3,3] row_mask:0xf bank_mask:0xf
	v_fmac_f32_dpp v59, v115, v95 quad_perm:[3,3,3,3] row_mask:0xf bank_mask:0xf
	v_fmac_f32_dpp v58, v119, v95 quad_perm:[3,3,3,3] row_mask:0xf bank_mask:0xf
	v_fmac_f32_dpp v57, v123, v95 quad_perm:[3,3,3,3] row_mask:0xf bank_mask:0xf
	v_fmac_f32_dpp v56, v127, v95 quad_perm:[3,3,3,3] row_mask:0xf bank_mask:0xf
	v_fmac_f32_dpp v55, v131, v95 quad_perm:[3,3,3,3] row_mask:0xf bank_mask:0xf
	ds_read_b128 v[96:99], v133 offset:128
	ds_read_b128 v[100:103], v133 offset:4224
	ds_read_b128 v[104:107], v133 offset:8320
	ds_read_b128 v[108:111], v133 offset:12416
	ds_read_b128 v[112:115], v133 offset:16512
	ds_read_b128 v[116:119], v133 offset:20608
	ds_read_b128 v[120:123], v133 offset:24704
	ds_read_b128 v[124:127], v133 offset:28800
	ds_read_b128 v[128:131], v133 offset:32896
	s_waitcnt lgkmcnt(9)
; #define LAS __attribute__((address_space(3)))
; __device__ __forceinline__ void adaln_unit(const Args& a, LAS unsigned char* lds, int unit, int tid, int wave, int lane) {
;     ...
;         for (int k = 0; k < 128; k += 16) {
;             float w[16];
; #pragma unroll
;             for (int e = 0; e < 16; ++e) w[e] = W[(size_t)(kh * 1024 + kb + k + e) * N + jc];
; #pragma unroll
;             for (int q = 0; q < 4; ++q)
; #pragma unroll
;                 for (int r = 0; r < 18; ++r) { const f32x4 s = *(const LAS f32x4*)(sc + r * 1024 + kb + k + 4 * q); acc[r] += s[0] * w[4 * q] + s[1] * w[4 * q + 1] + s[2] * w[4 * q + 2] + s[3] * w[4 * q + 3]; }
	v_fmac_f32_dpp v54, v2, v80 quad_perm:[0,0,0,0] row_mask:0xf bank_mask:0xf
	v_fmac_f32_dpp v53, v6, v80 quad_perm:[0,0,0,0] row_mask:0xf bank_mask:0xf
	v_fmac_f32_dpp v52, v10, v80 quad_perm:[0,0,0,0] row_mask:0xf bank_mask:0xf
	v_fmac_f32_dpp v51, v14, v80 quad_perm:[0,0,0,0] row_mask:0xf bank_mask:0xf
	v_fmac_f32_dpp v50, v18, v80 quad_perm:[0,0,0,0] row_mask:0xf bank_mask:0xf
	v_fmac_f32_dpp v49, v22, v80 quad_perm:[0,0,0,0] row_mask:0xf bank_mask:0xf
	v_fmac_f32_dpp v48, v26, v80 quad_perm:[0,0,0,0] row_mask:0xf bank_mask:0xf
	v_fmac_f32_dpp v47, v30, v80 quad_perm:[0,0,0,0] row_mask:0xf bank_mask:0xf
	v_fmac_f32_dpp v46, v34, v80 quad_perm:[0,0,0,0] row_mask:0xf bank_mask:0xf
	v_fmac_f32_dpp v54, v3, v81 quad_perm:[0,0,0,0] row_mask:0xf bank_mask:0xf
	v_fmac_f32_dpp v53, v7, v81 quad_perm:[0,0,0,0] row_mask:0xf bank_mask:0xf
	v_fmac_f32_dpp v52, v11, v81 quad_perm:[0,0,0,0] row_mask:0xf bank_mask:0xf
	v_fmac_f32_dpp v51, v15, v81 quad_perm:[0,0,0,0] row_mask:0xf bank_mask:0xf
	v_fmac_f32_dpp v50, v19, v81 quad_perm:[0,0,0,0] row_mask:0xf bank_mask:0xf
	v_fmac_f32_dpp v49, v23, v81 quad_perm:[0,0,0,0] row_mask:0xf bank_mask:0xf
	v_fmac_f32_dpp v48, v27, v81 quad_perm:[0,0,0,0] row_mask:0xf bank_mask:0xf
	v_fmac_f32_dpp v47, v31, v81 quad_perm:[0,0,0,0] row_mask:0xf bank_mask:0xf
	v_fmac_f32_dpp v46, v35, v81 quad_perm:[0,0,0,0] row_mask:0xf bank_mask:0xf
	v_fmac_f32_dpp v54, v4, v82 quad_perm:[0,0,0,0] row_mask:0xf bank_mask:0xf
	v_fmac_f32_dpp v53, v8, v82 quad_perm:[0,0,0,0] row_mask:0xf bank_mask:0xf
	v_fmac_f32_dpp v52, v12, v82 quad_perm:[0,0,0,0] row_mask:0xf bank_mask:0xf
	v_fmac_f32_dpp v51, v16, v82 quad_perm:[0,0,0,0] row_mask:0xf bank_mask:0xf
	v_fmac_f32_dpp v50, v20, v82 quad_perm:[0,0,0,0] row_mask:0xf bank_mask:0xf
	v_fmac_f32_dpp v49, v24, v82 quad_perm:[0,0,0,0] row_mask:0xf bank_mask:0xf
	v_fmac_f32_dpp v48, v28, v82 quad_perm:[0,0,0,0] row_mask:0xf bank_mask:0xf
	v_fmac_f32_dpp v47, v32, v82 quad_perm:[0,0,0,0] row_mask:0xf bank_mask:0xf
	v_fmac_f32_dpp v46, v36, v82 quad_perm:[0,0,0,0] row_mask:0xf bank_mask:0xf
	v_fmac_f32_dpp v54, v5, v83 quad_perm:[0,0,0,0] row_mask:0xf bank_mask:0xf
	v_fmac_f32_dpp v53, v9, v83 quad_perm:[0,0,0,0] row_mask:0xf bank_mask:0xf
	v_fmac_f32_dpp v52, v13, v83 quad_perm:[0,0,0,0] row_mask:0xf bank_mask:0xf
	v_fmac_f32_dpp v51, v17, v83 quad_perm:[0,0,0,0] row_mask:0xf bank_mask:0xf
	v_fmac_f32_dpp v50, v21, v83 quad_perm:[0,0,0,0] row_mask:0xf bank_mask:0xf
	v_fmac_f32_dpp v49, v25, v83 quad_perm:[0,0,0,0] row_mask:0xf bank_mask:0xf
	v_fmac_f32_dpp v48, v29, v83 quad_perm:[0,0,0,0] row_mask:0xf bank_mask:0xf
	v_fmac_f32_dpp v47, v33, v83 quad_perm:[0,0,0,0] row_mask:0xf bank_mask:0xf
	v_fmac_f32_dpp v46, v37, v83 quad_perm:[0,0,0,0] row_mask:0xf bank_mask:0xf
	v_fmac_f32_dpp v54, v2, v84 quad_perm:[1,1,1,1] row_mask:0xf bank_mask:0xf
	v_fmac_f32_dpp v53, v6, v84 quad_perm:[1,1,1,1] row_mask:0xf bank_mask:0xf
	v_fmac_f32_dpp v52, v10, v84 quad_perm:[1,1,1,1] row_mask:0xf bank_mask:0xf
	v_fmac_f32_dpp v51, v14, v84 quad_perm:[1,1,1,1] row_mask:0xf bank_mask:0xf
	v_fmac_f32_dpp v50, v18, v84 quad_perm:[1,1,1,1] row_mask:0xf bank_mask:0xf
	v_fmac_f32_dpp v49, v22, v84 quad_perm:[1,1,1,1] row_mask:0xf bank_mask:0xf
	v_fmac_f32_dpp v48, v26, v84 quad_perm:[1,1,1,1] row_mask:0xf bank_mask:0xf
	v_fmac_f32_dpp v47, v30, v84 quad_perm:[1,1,1,1] row_mask:0xf bank_mask:0xf
	v_fmac_f32_dpp v46, v34, v84 quad_perm:[1,1,1,1] row_mask:0xf bank_mask:0xf
	v_fmac_f32_dpp v54, v3, v85 quad_perm:[1,1,1,1] row_mask:0xf bank_mask:0xf
	v_fmac_f32_dpp v53, v7, v85 quad_perm:[1,1,1,1] row_mask:0xf bank_mask:0xf
	v_fmac_f32_dpp v52, v11, v85 quad_perm:[1,1,1,1] row_mask:0xf bank_mask:0xf
	v_fmac_f32_dpp v51, v15, v85 quad_perm:[1,1,1,1] row_mask:0xf bank_mask:0xf
	v_fmac_f32_dpp v50, v19, v85 quad_perm:[1,1,1,1] row_mask:0xf bank_mask:0xf
	v_fmac_f32_dpp v49, v23, v85 quad_perm:[1,1,1,1] row_mask:0xf bank_mask:0xf
	v_fmac_f32_dpp v48, v27, v85 quad_perm:[1,1,1,1] row_mask:0xf bank_mask:0xf
	v_fmac_f32_dpp v47, v31, v85 quad_perm:[1,1,1,1] row_mask:0xf bank_mask:0xf
	v_fmac_f32_dpp v46, v35, v85 quad_perm:[1,1,1,1] row_mask:0xf bank_mask:0xf
	v_fmac_f32_dpp v54, v4, v86 quad_perm:[1,1,1,1] row_mask:0xf bank_mask:0xf
	v_fmac_f32_dpp v53, v8, v86 quad_perm:[1,1,1,1] row_mask:0xf bank_mask:0xf
	v_fmac_f32_dpp v52, v12, v86 quad_perm:[1,1,1,1] row_mask:0xf bank_mask:0xf
	v_fmac_f32_dpp v51, v16, v86 quad_perm:[1,1,1,1] row_mask:0xf bank_mask:0xf
	v_fmac_f32_dpp v50, v20, v86 quad_perm:[1,1,1,1] row_mask:0xf bank_mask:0xf
	v_fmac_f32_dpp v49, v24, v86 quad_perm:[1,1,1,1] row_mask:0xf bank_mask:0xf
	v_fmac_f32_dpp v48, v28, v86 quad_perm:[1,1,1,1] row_mask:0xf bank_mask:0xf
	v_fmac_f32_dpp v47, v32, v86 quad_perm:[1,1,1,1] row_mask:0xf bank_mask:0xf
	v_fmac_f32_dpp v46, v36, v86 quad_perm:[1,1,1,1] row_mask:0xf bank_mask:0xf
	v_fmac_f32_dpp v54, v5, v87 quad_perm:[1,1,1,1] row_mask:0xf bank_mask:0xf
	v_fmac_f32_dpp v53, v9, v87 quad_perm:[1,1,1,1] row_mask:0xf bank_mask:0xf
	v_fmac_f32_dpp v52, v13, v87 quad_perm:[1,1,1,1] row_mask:0xf bank_mask:0xf
	v_fmac_f32_dpp v51, v17, v87 quad_perm:[1,1,1,1] row_mask:0xf bank_mask:0xf
	v_fmac_f32_dpp v50, v21, v87 quad_perm:[1,1,1,1] row_mask:0xf bank_mask:0xf
	v_fmac_f32_dpp v49, v25, v87 quad_perm:[1,1,1,1] row_mask:0xf bank_mask:0xf
	v_fmac_f32_dpp v48, v29, v87 quad_perm:[1,1,1,1] row_mask:0xf bank_mask:0xf
	v_fmac_f32_dpp v47, v33, v87 quad_perm:[1,1,1,1] row_mask:0xf bank_mask:0xf
	v_fmac_f32_dpp v46, v37, v87 quad_perm:[1,1,1,1] row_mask:0xf bank_mask:0xf
	v_fmac_f32_dpp v54, v2, v88 quad_perm:[2,2,2,2] row_mask:0xf bank_mask:0xf
; #define LAS __attribute__((address_space(3)))
; __device__ __forceinline__ void adaln_unit(const Args& a, LAS unsigned char* lds, int unit, int tid, int wave, int lane) {
;     ...
;         for (int k = 0; k < 128; k += 16) {
;             float w[16];
; #pragma unroll
;             for (int e = 0; e < 16; ++e) w[e] = W[(size_t)(kh * 1024 + kb + k + e) * N + jc];
; #pragma unroll
;             for (int q = 0; q < 4; ++q)
; #pragma unroll
;                 for (int r = 0; r < 18; ++r) { const f32x4 s = *(const LAS f32x4*)(sc + r * 1024 + kb + k + 4 * q); acc[r] += s[0] * w[4 * q] + s[1] * w[4 * q + 1] + s[2] * w[4 * q + 2] + s[3] * w[4 * q + 3]; }
;         }
;     }
; #pragma unroll
;     for (int r = 0; r < 18; ++r) red[(wave * 18 + r) * 64 + lane] = acc[r];
;     __syncthreads();
;     for (int i = tid; i < 18 * 64; i += NTHR) { const int r = i >> 6, l = i & 63; float s = 0.f;
	v_fmac_f32_dpp v53, v6, v88 quad_perm:[2,2,2,2] row_mask:0xf bank_mask:0xf
	v_fmac_f32_dpp v52, v10, v88 quad_perm:[2,2,2,2] row_mask:0xf bank_mask:0xf
	v_fmac_f32_dpp v51, v14, v88 quad_perm:[2,2,2,2] row_mask:0xf bank_mask:0xf
	v_fmac_f32_dpp v50, v18, v88 quad_perm:[2,2,2,2] row_mask:0xf bank_mask:0xf
	v_fmac_f32_dpp v49, v22, v88 quad_perm:[2,2,2,2] row_mask:0xf bank_mask:0xf
	v_fmac_f32_dpp v48, v26, v88 quad_perm:[2,2,2,2] row_mask:0xf bank_mask:0xf
	v_fmac_f32_dpp v47, v30, v88 quad_perm:[2,2,2,2] row_mask:0xf bank_mask:0xf
	v_fmac_f32_dpp v46, v34, v88 quad_perm:[2,2,2,2] row_mask:0xf bank_mask:0xf
	v_fmac_f32_dpp v54, v3, v89 quad_perm:[2,2,2,2] row_mask:0xf bank_mask:0xf
	v_fmac_f32_dpp v53, v7, v89 quad_perm:[2,2,2,2] row_mask:0xf bank_mask:0xf
	v_fmac_f32_dpp v52, v11, v89 quad_perm:[2,2,2,2] row_mask:0xf bank_mask:0xf
	v_fmac_f32_dpp v51, v15, v89 quad_perm:[2,2,2,2] row_mask:0xf bank_mask:0xf
	v_fmac_f32_dpp v50, v19, v89 quad_perm:[2,2,2,2] row_mask:0xf bank_mask:0xf
	v_fmac_f32_dpp v49, v23, v89 quad_perm:[2,2,2,2] row_mask:0xf bank_mask:0xf
	v_fmac_f32_dpp v48, v27, v89 quad_perm:[2,2,2,2] row_mask:0xf bank_mask:0xf
	v_fmac_f32_dpp v47, v31, v89 quad_perm:[2,2,2,2] row_mask:0xf bank_mask:0xf
	v_fmac_f32_dpp v46, v35, v89 quad_perm:[2,2,2,2] row_mask:0xf bank_mask:0xf
	v_fmac_f32_dpp v54, v4, v90 quad_perm:[2,2,2,2] row_mask:0xf bank_mask:0xf
	v_fmac_f32_dpp v53, v8, v90 quad_perm:[2,2,2,2] row_mask:0xf bank_mask:0xf
	v_fmac_f32_dpp v52, v12, v90 quad_perm:[2,2,2,2] row_mask:0xf bank_mask:0xf
	v_fmac_f32_dpp v51, v16, v90 quad_perm:[2,2,2,2] row_mask:0xf bank_mask:0xf
	v_fmac_f32_dpp v50, v20, v90 quad_perm:[2,2,2,2] row_mask:0xf bank_mask:0xf
	v_fmac_f32_dpp v49, v24, v90 quad_perm:[2,2,2,2] row_mask:0xf bank_mask:0xf
	v_fmac_f32_dpp v48, v28, v90 quad_perm:[2,2,2,2] row_mask:0xf bank_mask:0xf
	v_fmac_f32_dpp v47, v32, v90 quad_perm:[2,2,2,2] row_mask:0xf bank_mask:0xf
	v_fmac_f32_dpp v46, v36, v90 quad_perm:[2,2,2,2] row_mask:0xf bank_mask:0xf
	v_fmac_f32_dpp v54, v5, v91 quad_perm:[2,2,2,2] row_mask:0xf bank_mask:0xf
	v_fmac_f32_dpp v53, v9, v91 quad_perm:[2,2,2,2] row_mask:0xf bank_mask:0xf
	v_fmac_f32_dpp v52, v13, v91 quad_perm:[2,2,2,2] row_mask:0xf bank_mask:0xf
	v_fmac_f32_dpp v51, v17, v91 quad_perm:[2,2,2,2] row_mask:0xf bank_mask:0xf
	v_fmac_f32_dpp v50, v21, v91 quad_perm:[2,2,2,2] row_mask:0xf bank_mask:0xf
	v_fmac_f32_dpp v49, v25, v91 quad_perm:[2,2,2,2] row_mask:0xf bank_mask:0xf
	v_fmac_f32_dpp v48, v29, v91 quad_perm:[2,2,2,2] row_mask:0xf bank_mask:0xf
	v_fmac_f32_dpp v47, v33, v91 quad_perm:[2,2,2,2] row_mask:0xf bank_mask:0xf
	v_fmac_f32_dpp v46, v37, v91 quad_perm:[2,2,2,2] row_mask:0xf bank_mask:0xf
	v_fmac_f32_dpp v54, v2, v92 quad_perm:[3,3,3,3] row_mask:0xf bank_mask:0xf
	v_fmac_f32_dpp v53, v6, v92 quad_perm:[3,3,3,3] row_mask:0xf bank_mask:0xf
	v_fmac_f32_dpp v52, v10, v92 quad_perm:[3,3,3,3] row_mask:0xf bank_mask:0xf
	v_fmac_f32_dpp v51, v14, v92 quad_perm:[3,3,3,3] row_mask:0xf bank_mask:0xf
	v_fmac_f32_dpp v50, v18, v92 quad_perm:[3,3,3,3] row_mask:0xf bank_mask:0xf
	v_fmac_f32_dpp v49, v22, v92 quad_perm:[3,3,3,3] row_mask:0xf bank_mask:0xf
	v_fmac_f32_dpp v48, v26, v92 quad_perm:[3,3,3,3] row_mask:0xf bank_mask:0xf
	v_fmac_f32_dpp v47, v30, v92 quad_perm:[3,3,3,3] row_mask:0xf bank_mask:0xf
	v_fmac_f32_dpp v46, v34, v92 quad_perm:[3,3,3,3] row_mask:0xf bank_mask:0xf
	v_fmac_f32_dpp v54, v3, v93 quad_perm:[3,3,3,3] row_mask:0xf bank_mask:0xf
	v_fmac_f32_dpp v53, v7, v93 quad_perm:[3,3,3,3] row_mask:0xf bank_mask:0xf
	v_fmac_f32_dpp v52, v11, v93 quad_perm:[3,3,3,3] row_mask:0xf bank_mask:0xf
	v_fmac_f32_dpp v51, v15, v93 quad_perm:[3,3,3,3] row_mask:0xf bank_mask:0xf
	v_fmac_f32_dpp v50, v19, v93 quad_perm:[3,3,3,3] row_mask:0xf bank_mask:0xf
	v_fmac_f32_dpp v49, v23, v93 quad_perm:[3,3,3,3] row_mask:0xf bank_mask:0xf
	v_fmac_f32_dpp v48, v27, v93 quad_perm:[3,3,3,3] row_mask:0xf bank_mask:0xf
	v_fmac_f32_dpp v47, v31, v93 quad_perm:[3,3,3,3] row_mask:0xf bank_mask:0xf
	v_fmac_f32_dpp v46, v35, v93 quad_perm:[3,3,3,3] row_mask:0xf bank_mask:0xf
	v_fmac_f32_dpp v54, v4, v94 quad_perm:[3,3,3,3] row_mask:0xf bank_mask:0xf
	v_fmac_f32_dpp v53, v8, v94 quad_perm:[3,3,3,3] row_mask:0xf bank_mask:0xf
	v_fmac_f32_dpp v52, v12, v94 quad_perm:[3,3,3,3] row_mask:0xf bank_mask:0xf
	v_fmac_f32_dpp v51, v16, v94 quad_perm:[3,3,3,3] row_mask:0xf bank_mask:0xf
	v_fmac_f32_dpp v50, v20, v94 quad_perm:[3,3,3,3] row_mask:0xf bank_mask:0xf
	v_fmac_f32_dpp v49, v24, v94 quad_perm:[3,3,3,3] row_mask:0xf bank_mask:0xf
	v_fmac_f32_dpp v48, v28, v94 quad_perm:[3,3,3,3] row_mask:0xf bank_mask:0xf
	v_fmac_f32_dpp v47, v32, v94 quad_perm:[3,3,3,3] row_mask:0xf bank_mask:0xf
	v_fmac_f32_dpp v46, v36, v94 quad_perm:[3,3,3,3] row_mask:0xf bank_mask:0xf
	v_fmac_f32_dpp v54, v5, v95 quad_perm:[3,3,3,3] row_mask:0xf bank_mask:0xf
	v_fmac_f32_dpp v53, v9, v95 quad_perm:[3,3,3,3] row_mask:0xf bank_mask:0xf
	v_fmac_f32_dpp v52, v13, v95 quad_perm:[3,3,3,3] row_mask:0xf bank_mask:0xf
	v_fmac_f32_dpp v51, v17, v95 quad_perm:[3,3,3,3] row_mask:0xf bank_mask:0xf
	v_fmac_f32_dpp v50, v21, v95 quad_perm:[3,3,3,3] row_mask:0xf bank_mask:0xf
	v_fmac_f32_dpp v49, v25, v95 quad_perm:[3,3,3,3] row_mask:0xf bank_mask:0xf
	v_fmac_f32_dpp v48, v29, v95 quad_perm:[3,3,3,3] row_mask:0xf bank_mask:0xf
	v_fmac_f32_dpp v47, v33, v95 quad_perm:[3,3,3,3] row_mask:0xf bank_mask:0xf
	v_fmac_f32_dpp v46, v37, v95 quad_perm:[3,3,3,3] row_mask:0xf bank_mask:0xf
	ds_read_b128 v[2:5], v133 offset:36992
	ds_read_b128 v[6:9], v133 offset:41088
	ds_read_b128 v[10:13], v133 offset:45184
	ds_read_b128 v[14:17], v133 offset:49280
	ds_read_b128 v[18:21], v133 offset:53376
	ds_read_b128 v[22:25], v133 offset:57472
	ds_read_b128 v[26:29], v133 offset:61568
	ds_read_b128 v[30:33], v134 offset:128
	ds_read_b128 v[34:37], v134 offset:4224
	v_add_u32_e32 v133, 0x80, v133
	v_add_u32_e32 v134, 0x80, v134
	s_add_i32 s82, s82, 1
	s_cmp_lt_u32 s82, 4
	s_cbranch_scc1 .Lada_loop
	s_waitcnt lgkmcnt(0)
	s_movk_i32 s58, 0x400
	s_mov_b64 s[82:83], 0
	s_and_b64 vcc, exec, s[80:81]
	s_cbranch_vccz .LBB0_12
	ds_write2st64_b32 v146, v63, v62 offset1:1
	ds_write2st64_b32 v146, v61, v60 offset0:2 offset1:3
	ds_write2st64_b32 v146, v59, v58 offset0:4 offset1:5
	ds_write2st64_b32 v146, v57, v56 offset0:6 offset1:7
	ds_write2st64_b32 v146, v55, v54 offset0:8 offset1:9
	ds_write2st64_b32 v146, v53, v52 offset0:10 offset1:11
	ds_write2st64_b32 v146, v51, v50 offset0:12 offset1:13
	ds_write2st64_b32 v146, v49, v48 offset0:14 offset1:15
	ds_write2st64_b32 v146, v47, v46 offset0:16 offset1:17
	s_waitcnt lgkmcnt(0)
	s_barrier
	s_and_saveexec_b64 s[78:79], s[4:5]
	s_cbranch_execz .LBB0_10
	v_or_b32_e32 v2, s28, v147
	v_ashrrev_i32_e32 v3, 31, v2
	s_mov_b64 s[80:81], 0
	v_mov_b32_e32 v12, v41
	s_branch .LBB0_25
